# 12-barrier K-loops (v046) + s_nop 0 restored between the m0 write and the LDS-DMA at two sites (M0 hazard wait state)
# baseline (speedup 1.0000x reference)
.LBB0_124:
	s_nop 0
	s_ashr_i32 s79, s78, 31
	s_lshl_b64 s[10:11], s[78:79], 19
	s_add_u32 s80, s54, s10
	v_cmp_lt_i64_e32 vcc, s[72:73], v[178:179]
	s_addc_u32 s81, s55, s11
	s_and_b64 s[10:11], vcc, exec
	s_cselect_b32 s1, s81, s87
	s_cselect_b32 s10, s80, s86
	s_ashr_i32 s77, s76, 31
	s_lshl_b64 s[36:37], s[76:77], 19
	s_add_u32 s72, s66, s36
	s_addc_u32 s73, s59, s37
	s_and_b64 s[36:37], vcc, exec
	s_cselect_b32 s11, s73, s83
	s_cselect_b32 s25, s72, s82
	s_add_u32 s86, s86, 0x40080
	s_addc_u32 s87, s87, 0
	s_add_u32 s33, s82, 0x100
	s_addc_u32 s36, s83, 0
	s_mov_b32 s37, -2
	s_add_u32 s27, s86, 0xfffc0080
	s_addc_u32 s56, s87, -1
	s_add_i32 s57, 0, 0x10000
	ds_read_b128 v[64:67], v217
	ds_read_b128 v[68:71], v217 offset:1024
	ds_read_b128 v[72:75], v217 offset:2048
	ds_read_b128 v[76:79], v217 offset:3072
	s_cmp_eq_u32 s37, 12
	s_cselect_b32 vcc_hi, s1, s56
	s_cselect_b32 vcc_lo, s10, s27
	s_cselect_b32 s83, s11, s36
	s_cselect_b32 s82, s25, s33
	s_add_i32 m0, s75, 0xc000
	ds_read_b128 v[80:83], v220
	ds_read_b128 v[84:87], v220 offset:1024
	ds_read_b128 v[88:91], v220 offset:2048
	ds_read_b128 v[92:95], v220 offset:3072
	ds_read_b128 v[188:191], v220 offset:4096
	ds_read_b128 v[192:195], v220 offset:5120
	ds_read_b128 v[196:199], v220 offset:6144
	ds_read_b128 v[200:203], v220 offset:7168
	global_load_lds_dwordx4 v164, s[86:87]
	s_add_i32 m0, s75, 0xe000
	s_nop 0
	global_load_lds_dwordx4 v166, s[86:87]
	s_waitcnt lgkmcnt(0)
	s_barrier
	v_mfma_f32_16x16x32_bf16 v[146:149], v[64:67], v[80:83], 0
	v_mfma_f32_16x16x32_bf16 v[116:119], v[72:75], v[80:83], 0
	v_mfma_f32_16x16x32_bf16 v[158:161], v[64:67], v[88:91], 0
	v_mfma_f32_16x16x32_bf16 v[124:127], v[72:75], v[88:91], 0
	v_mfma_f32_16x16x32_bf16 v[154:157], v[64:67], v[188:191], 0
	v_mfma_f32_16x16x32_bf16 v[112:115], v[72:75], v[188:191], 0
	v_mfma_f32_16x16x32_bf16 v[150:153], v[64:67], v[196:199], 0
	v_mfma_f32_16x16x32_bf16 v[120:123], v[72:75], v[196:199], 0
	v_mfma_f32_16x16x32_bf16 v[146:149], v[68:71], v[84:87], v[146:149]
	v_mfma_f32_16x16x32_bf16 v[116:119], v[76:79], v[84:87], v[116:119]
	v_mfma_f32_16x16x32_bf16 v[158:161], v[68:71], v[92:95], v[158:161]
	v_mfma_f32_16x16x32_bf16 v[124:127], v[76:79], v[92:95], v[124:127]
	v_mfma_f32_16x16x32_bf16 v[154:157], v[68:71], v[192:195], v[154:157]
	v_mfma_f32_16x16x32_bf16 v[112:115], v[76:79], v[192:195], v[112:115]
	v_mfma_f32_16x16x32_bf16 v[150:153], v[68:71], v[200:203], v[150:153]
	v_mfma_f32_16x16x32_bf16 v[120:123], v[76:79], v[200:203], v[120:123]
	s_barrier
	s_add_i32 s27, 0, 0x14000
	s_add_i32 s56, s57, s74
	ds_read_b128 v[204:207], v217 offset:16384
	ds_read_b128 v[222:225], v217 offset:17408
	ds_read_b128 v[228:231], v217 offset:18432
	ds_read_b128 v[232:235], v217 offset:19456
	s_mov_b32 m0, s56
	s_nop 0
	global_load_lds_dwordx4 v144, s[82:83]
	s_add_i32 m0, s56, 0x2000
	s_nop 0
	global_load_lds_dwordx4 v162, s[82:83]
	s_waitcnt lgkmcnt(0)
	s_barrier
	v_mfma_f32_16x16x32_bf16 v[140:143], v[204:207], v[80:83], 0
	v_mfma_f32_16x16x32_bf16 v[80:83], v[228:231], v[80:83], 0
	v_mfma_f32_16x16x32_bf16 v[140:143], v[222:225], v[84:87], v[140:143]
	v_mfma_f32_16x16x32_bf16 v[80:83], v[232:235], v[84:87], v[80:83]
	v_mfma_f32_16x16x32_bf16 v[84:87], v[204:207], v[88:91], 0
	v_mfma_f32_16x16x32_bf16 v[88:91], v[228:231], v[88:91], 0
	v_mfma_f32_16x16x32_bf16 v[100:103], v[228:231], v[188:191], 0
	v_mfma_f32_16x16x32_bf16 v[104:107], v[204:207], v[196:199], 0
	v_mfma_f32_16x16x32_bf16 v[96:99], v[228:231], v[196:199], 0
	v_mfma_f32_16x16x32_bf16 v[84:87], v[222:225], v[92:95], v[84:87]
	v_mfma_f32_16x16x32_bf16 v[88:91], v[232:235], v[92:95], v[88:91]
	v_mfma_f32_16x16x32_bf16 v[92:95], v[204:207], v[188:191], 0
	v_mfma_f32_16x16x32_bf16 v[100:103], v[232:235], v[192:195], v[100:103]
	v_mfma_f32_16x16x32_bf16 v[128:131], v[222:225], v[200:203], v[104:107]
	v_mfma_f32_16x16x32_bf16 v[96:99], v[232:235], v[200:203], v[96:99]
	v_mfma_f32_16x16x32_bf16 v[92:95], v[222:225], v[192:195], v[92:95]
	s_barrier
	s_mov_b32 m0, s75
	ds_read_b128 v[104:107], v220 offset:16384
	ds_read_b128 v[108:111], v220 offset:17408
	ds_read_b128 v[132:135], v220 offset:18432
	ds_read_b128 v[136:139], v220 offset:19456
	ds_read_b128 v[188:191], v220 offset:20480
	ds_read_b128 v[192:195], v220 offset:21504
	ds_read_b128 v[196:199], v220 offset:22528
	ds_read_b128 v[200:203], v220 offset:23552
	global_load_lds_dwordx4 v144, vcc
	s_mov_b32 m0, s85
	s_nop 0
	global_load_lds_dwordx4 v162, vcc
	s_add_u32 s56, s82, 0x40000
	s_addc_u32 s57, s83, 0
	s_add_i32 s27, s27, s74
	s_mov_b32 m0, s27
	s_nop 0
	global_load_lds_dwordx4 v144, s[56:57]
	s_add_i32 m0, s27, 0x2000
	s_nop 0
	global_load_lds_dwordx4 v162, s[56:57]
	s_waitcnt lgkmcnt(0)
	s_waitcnt vmcnt(6)
	s_barrier
	v_mfma_f32_16x16x32_bf16 v[48:51], v[64:67], v[104:107], 0
	v_mfma_f32_16x16x32_bf16 v[20:23], v[72:75], v[104:107], 0
	v_mfma_f32_16x16x32_bf16 v[60:63], v[64:67], v[132:135], 0
	v_mfma_f32_16x16x32_bf16 v[28:31], v[72:75], v[132:135], 0
	v_mfma_f32_16x16x32_bf16 v[56:59], v[64:67], v[188:191], 0
	v_mfma_f32_16x16x32_bf16 v[16:19], v[72:75], v[188:191], 0
	v_mfma_f32_16x16x32_bf16 v[52:55], v[64:67], v[196:199], 0
	v_mfma_f32_16x16x32_bf16 v[24:27], v[72:75], v[196:199], 0
	v_mfma_f32_16x16x32_bf16 v[48:51], v[68:71], v[108:111], v[48:51]
	v_mfma_f32_16x16x32_bf16 v[20:23], v[76:79], v[108:111], v[20:23]
	v_mfma_f32_16x16x32_bf16 v[60:63], v[68:71], v[136:139], v[60:63]
	v_mfma_f32_16x16x32_bf16 v[28:31], v[76:79], v[136:139], v[28:31]
	v_mfma_f32_16x16x32_bf16 v[56:59], v[68:71], v[192:195], v[56:59]
	v_mfma_f32_16x16x32_bf16 v[16:19], v[76:79], v[192:195], v[16:19]
	v_mfma_f32_16x16x32_bf16 v[52:55], v[68:71], v[200:203], v[52:55]
	v_mfma_f32_16x16x32_bf16 v[24:27], v[76:79], v[200:203], v[24:27]
	v_mfma_f32_16x16x32_bf16 v[44:47], v[204:207], v[104:107], 0
	v_mfma_f32_16x16x32_bf16 v[12:15], v[228:231], v[104:107], 0
	v_mfma_f32_16x16x32_bf16 v[40:43], v[204:207], v[132:135], 0
	v_mfma_f32_16x16x32_bf16 v[8:11], v[228:231], v[132:135], 0
	v_mfma_f32_16x16x32_bf16 v[36:39], v[204:207], v[188:191], 0
	v_mfma_f32_16x16x32_bf16 v[4:7], v[228:231], v[188:191], 0
	v_mfma_f32_16x16x32_bf16 v[32:35], v[204:207], v[196:199], 0
	v_mfma_f32_16x16x32_bf16 v[0:3], v[228:231], v[196:199], 0
	v_mfma_f32_16x16x32_bf16 v[44:47], v[222:225], v[108:111], v[44:47]
	v_mfma_f32_16x16x32_bf16 v[12:15], v[232:235], v[108:111], v[12:15]
	v_mfma_f32_16x16x32_bf16 v[40:43], v[222:225], v[136:139], v[40:43]
	v_mfma_f32_16x16x32_bf16 v[8:11], v[232:235], v[136:139], v[8:11]
	v_mfma_f32_16x16x32_bf16 v[36:39], v[222:225], v[192:195], v[36:39]
	v_mfma_f32_16x16x32_bf16 v[4:7], v[232:235], v[192:195], v[4:7]
	v_mfma_f32_16x16x32_bf16 v[32:35], v[222:225], v[200:203], v[32:35]
	v_mfma_f32_16x16x32_bf16 v[0:3], v[232:235], v[200:203], v[0:3]
	s_barrier
	s_add_i32 s27, 0, 0x18000
	ds_read_b128 v[64:67], v217 offset:32768
	ds_read_b128 v[68:71], v217 offset:33792
	ds_read_b128 v[72:75], v217 offset:34816
	ds_read_b128 v[76:79], v217 offset:35840
	s_add_u32 s56, vcc_lo, 0x40000
	s_addc_u32 s57, vcc_hi, 0
	s_mov_b32 m0, s98
	ds_read_b128 v[104:107], v220 offset:32768
	ds_read_b128 v[108:111], v220 offset:33792
	ds_read_b128 v[132:135], v220 offset:34816
	ds_read_b128 v[188:191], v220 offset:35840
	ds_read_b128 v[192:195], v220 offset:36864
	ds_read_b128 v[196:199], v220 offset:37888
	ds_read_b128 v[200:203], v220 offset:38912
	ds_read_b128 v[204:207], v220 offset:39936
	global_load_lds_dwordx4 v144, s[56:57]
	s_mov_b32 m0, s29
	s_nop 0
	global_load_lds_dwordx4 v162, s[56:57]
	s_waitcnt lgkmcnt(0)
	s_barrier
	v_mfma_f32_16x16x32_bf16 v[136:139], v[64:67], v[104:107], v[146:149]
	v_mfma_f32_16x16x32_bf16 v[146:149], v[68:71], v[108:111], v[136:139]
	v_mfma_f32_16x16x32_bf16 v[136:139], v[64:67], v[132:135], v[158:161]
	v_mfma_f32_16x16x32_bf16 v[158:161], v[68:71], v[188:191], v[136:139]
	v_mfma_f32_16x16x32_bf16 v[136:139], v[64:67], v[192:195], v[154:157]
	v_mfma_f32_16x16x32_bf16 v[116:119], v[72:75], v[104:107], v[116:119]
	v_mfma_f32_16x16x32_bf16 v[124:127], v[72:75], v[132:135], v[124:127]
	v_mfma_f32_16x16x32_bf16 v[154:157], v[68:71], v[196:199], v[136:139]
	v_mfma_f32_16x16x32_bf16 v[112:115], v[72:75], v[192:195], v[112:115]
	v_mfma_f32_16x16x32_bf16 v[136:139], v[64:67], v[200:203], v[150:153]
	v_mfma_f32_16x16x32_bf16 v[120:123], v[72:75], v[200:203], v[120:123]
	v_mfma_f32_16x16x32_bf16 v[116:119], v[76:79], v[108:111], v[116:119]
	v_mfma_f32_16x16x32_bf16 v[124:127], v[76:79], v[188:191], v[124:127]
	v_mfma_f32_16x16x32_bf16 v[112:115], v[76:79], v[196:199], v[112:115]
	v_mfma_f32_16x16x32_bf16 v[150:153], v[68:71], v[204:207], v[136:139]
	v_mfma_f32_16x16x32_bf16 v[120:123], v[76:79], v[204:207], v[120:123]
	s_barrier
	s_nop 0
	s_add_i32 s58, 0, 0x1c000
	s_add_i32 s27, s27, s74
	ds_read_b128 v[222:225], v217 offset:49152
	ds_read_b128 v[228:231], v217 offset:50176
	ds_read_b128 v[232:235], v217 offset:51200
	ds_read_b128 v[236:239], v217 offset:52224
	s_add_u32 s56, s82, s18
	s_addc_u32 s57, s83, s19
	s_mov_b32 m0, s27
	s_nop 0
	global_load_lds_dwordx4 v144, s[56:57]
	s_add_u32 s56, s82, s18
	s_addc_u32 s57, s83, s19
	s_add_i32 m0, s27, 0x2000
	s_nop 0
	global_load_lds_dwordx4 v162, s[56:57]
	s_waitcnt lgkmcnt(0)
	s_barrier
	v_mfma_f32_16x16x32_bf16 v[136:139], v[222:225], v[104:107], v[140:143]
	v_mfma_f32_16x16x32_bf16 v[80:83], v[232:235], v[104:107], v[80:83]
	v_mfma_f32_16x16x32_bf16 v[140:143], v[228:231], v[108:111], v[136:139]
	v_mfma_f32_16x16x32_bf16 v[108:111], v[236:239], v[108:111], v[80:83]
	v_mfma_f32_16x16x32_bf16 v[80:83], v[222:225], v[132:135], v[84:87]
	v_mfma_f32_16x16x32_bf16 v[136:139], v[228:231], v[188:191], v[80:83]
	v_mfma_f32_16x16x32_bf16 v[80:83], v[232:235], v[132:135], v[88:91]
	v_mfma_f32_16x16x32_bf16 v[104:107], v[236:239], v[188:191], v[80:83]
	v_mfma_f32_16x16x32_bf16 v[80:83], v[222:225], v[192:195], v[92:95]
	v_mfma_f32_16x16x32_bf16 v[132:135], v[228:231], v[196:199], v[80:83]
	v_mfma_f32_16x16x32_bf16 v[80:83], v[232:235], v[192:195], v[100:103]
	v_mfma_f32_16x16x32_bf16 v[100:103], v[236:239], v[196:199], v[80:83]
	v_mfma_f32_16x16x32_bf16 v[80:83], v[222:225], v[200:203], v[128:131]
	v_mfma_f32_16x16x32_bf16 v[128:131], v[228:231], v[204:207], v[80:83]
	v_mfma_f32_16x16x32_bf16 v[80:83], v[232:235], v[200:203], v[96:99]
	v_mfma_f32_16x16x32_bf16 v[96:99], v[236:239], v[204:207], v[80:83]
	s_barrier
	s_nop 0
	s_mov_b32 m0, s31
	s_add_u32 s56, vcc_lo, s18
	s_addc_u32 s57, vcc_hi, s19
	s_nop 2
	ds_read_b128 v[80:83], v220 offset:49152
	ds_read_b128 v[84:87], v220 offset:50176
	ds_read_b128 v[88:91], v220 offset:51200
	ds_read_b128 v[92:95], v220 offset:52224
	ds_read_b128 v[188:191], v220 offset:53248
	ds_read_b128 v[192:195], v220 offset:54272
	ds_read_b128 v[196:199], v220 offset:55296
	ds_read_b128 v[200:203], v220 offset:56320
	global_load_lds_dwordx4 v144, s[56:57]
	s_add_u32 s56, vcc_lo, s18
	s_addc_u32 s57, vcc_hi, s19
	s_mov_b32 m0, s34
	s_nop 0
	global_load_lds_dwordx4 v162, s[56:57]
	s_add_u32 s56, s82, 0x40080
	s_addc_u32 s57, s83, 0
	s_add_i32 s27, s58, s74
	s_mov_b32 m0, s27
	s_nop 0
	global_load_lds_dwordx4 v144, s[56:57]
	s_add_i32 m0, s27, 0x2000
	s_nop 0
	global_load_lds_dwordx4 v162, s[56:57]
	s_waitcnt lgkmcnt(0)
	s_waitcnt vmcnt(6)
	s_barrier
	v_mfma_f32_16x16x32_bf16 v[48:51], v[64:67], v[80:83], v[48:51]
	v_mfma_f32_16x16x32_bf16 v[20:23], v[72:75], v[80:83], v[20:23]
	v_mfma_f32_16x16x32_bf16 v[60:63], v[64:67], v[88:91], v[60:63]
	v_mfma_f32_16x16x32_bf16 v[28:31], v[72:75], v[88:91], v[28:31]
	v_mfma_f32_16x16x32_bf16 v[56:59], v[64:67], v[188:191], v[56:59]
	v_mfma_f32_16x16x32_bf16 v[16:19], v[72:75], v[188:191], v[16:19]
	v_mfma_f32_16x16x32_bf16 v[52:55], v[64:67], v[196:199], v[52:55]
	v_mfma_f32_16x16x32_bf16 v[24:27], v[72:75], v[196:199], v[24:27]
	v_mfma_f32_16x16x32_bf16 v[48:51], v[68:71], v[84:87], v[48:51]
	v_mfma_f32_16x16x32_bf16 v[20:23], v[76:79], v[84:87], v[20:23]
	v_mfma_f32_16x16x32_bf16 v[60:63], v[68:71], v[92:95], v[60:63]
	v_mfma_f32_16x16x32_bf16 v[28:31], v[76:79], v[92:95], v[28:31]
	v_mfma_f32_16x16x32_bf16 v[56:59], v[68:71], v[192:195], v[56:59]
	v_mfma_f32_16x16x32_bf16 v[16:19], v[76:79], v[192:195], v[16:19]
	v_mfma_f32_16x16x32_bf16 v[52:55], v[68:71], v[200:203], v[52:55]
	v_mfma_f32_16x16x32_bf16 v[24:27], v[76:79], v[200:203], v[24:27]
	v_mfma_f32_16x16x32_bf16 v[44:47], v[222:225], v[80:83], v[44:47]
	v_mfma_f32_16x16x32_bf16 v[12:15], v[232:235], v[80:83], v[12:15]
	v_mfma_f32_16x16x32_bf16 v[40:43], v[222:225], v[88:91], v[40:43]
	v_mfma_f32_16x16x32_bf16 v[8:11], v[232:235], v[88:91], v[8:11]
	v_mfma_f32_16x16x32_bf16 v[36:39], v[222:225], v[188:191], v[36:39]
	v_mfma_f32_16x16x32_bf16 v[4:7], v[232:235], v[188:191], v[4:7]
	v_mfma_f32_16x16x32_bf16 v[32:35], v[222:225], v[196:199], v[32:35]
	v_mfma_f32_16x16x32_bf16 v[0:3], v[232:235], v[196:199], v[0:3]
	v_mfma_f32_16x16x32_bf16 v[44:47], v[228:231], v[84:87], v[44:47]
	v_mfma_f32_16x16x32_bf16 v[12:15], v[236:239], v[84:87], v[12:15]
	v_mfma_f32_16x16x32_bf16 v[40:43], v[228:231], v[92:95], v[40:43]
	v_mfma_f32_16x16x32_bf16 v[8:11], v[236:239], v[92:95], v[8:11]
	v_mfma_f32_16x16x32_bf16 v[36:39], v[228:231], v[192:195], v[36:39]
	v_mfma_f32_16x16x32_bf16 v[4:7], v[236:239], v[192:195], v[4:7]
	v_mfma_f32_16x16x32_bf16 v[32:35], v[228:231], v[200:203], v[32:35]
	v_mfma_f32_16x16x32_bf16 v[0:3], v[236:239], v[200:203], v[0:3]
	s_barrier
	s_add_i32 s37, s37, 2
	s_add_u32 s86, s86, 0x100
	s_addc_u32 s87, s87, 0
	s_add_u32 s33, s33, 0x100
	s_addc_u32 s36, s36, 0
	s_cmp_gt_u32 s37, 13
.LBB0_125:
	s_nop 0
	s_add_u32 s27, s86, 0xfffc0080
	s_addc_u32 s56, s87, -1
	s_add_i32 s57, 0, 0x10000
	ds_read_b128 v[64:67], v217
	ds_read_b128 v[68:71], v217 offset:1024
	ds_read_b128 v[72:75], v217 offset:2048
	ds_read_b128 v[76:79], v217 offset:3072
	s_cmp_eq_u32 s37, 12
	s_cselect_b32 vcc_hi, s1, s56
	s_cselect_b32 vcc_lo, s10, s27
	s_cselect_b32 s83, s11, s36
	s_cselect_b32 s82, s25, s33
	s_add_i32 m0, s75, 0xc000
	ds_read_b128 v[80:83], v220
	ds_read_b128 v[84:87], v220 offset:1024
	ds_read_b128 v[88:91], v220 offset:2048
	ds_read_b128 v[92:95], v220 offset:3072
	ds_read_b128 v[188:191], v220 offset:4096
	ds_read_b128 v[192:195], v220 offset:5120
	ds_read_b128 v[196:199], v220 offset:6144
	ds_read_b128 v[200:203], v220 offset:7168
	global_load_lds_dwordx4 v164, s[86:87]
	s_add_i32 m0, s75, 0xe000
	s_nop 0
	global_load_lds_dwordx4 v166, s[86:87]
	s_waitcnt lgkmcnt(0)
	s_barrier
	v_mfma_f32_16x16x32_bf16 v[146:149], v[64:67], v[80:83], v[146:149]
	v_mfma_f32_16x16x32_bf16 v[116:119], v[72:75], v[80:83], v[116:119]
	v_mfma_f32_16x16x32_bf16 v[158:161], v[64:67], v[88:91], v[158:161]
	v_mfma_f32_16x16x32_bf16 v[124:127], v[72:75], v[88:91], v[124:127]
	v_mfma_f32_16x16x32_bf16 v[154:157], v[64:67], v[188:191], v[154:157]
	v_mfma_f32_16x16x32_bf16 v[112:115], v[72:75], v[188:191], v[112:115]
	v_mfma_f32_16x16x32_bf16 v[150:153], v[64:67], v[196:199], v[150:153]
	v_mfma_f32_16x16x32_bf16 v[120:123], v[72:75], v[196:199], v[120:123]
	v_mfma_f32_16x16x32_bf16 v[146:149], v[68:71], v[84:87], v[146:149]
	v_mfma_f32_16x16x32_bf16 v[116:119], v[76:79], v[84:87], v[116:119]
	v_mfma_f32_16x16x32_bf16 v[158:161], v[68:71], v[92:95], v[158:161]
	v_mfma_f32_16x16x32_bf16 v[124:127], v[76:79], v[92:95], v[124:127]
	v_mfma_f32_16x16x32_bf16 v[154:157], v[68:71], v[192:195], v[154:157]
	v_mfma_f32_16x16x32_bf16 v[112:115], v[76:79], v[192:195], v[112:115]
	v_mfma_f32_16x16x32_bf16 v[150:153], v[68:71], v[200:203], v[150:153]
	v_mfma_f32_16x16x32_bf16 v[120:123], v[76:79], v[200:203], v[120:123]
	s_barrier
	s_add_i32 s27, 0, 0x14000
	s_add_i32 s56, s57, s74
	ds_read_b128 v[204:207], v217 offset:16384
	ds_read_b128 v[222:225], v217 offset:17408
	ds_read_b128 v[228:231], v217 offset:18432
	ds_read_b128 v[232:235], v217 offset:19456
	s_mov_b32 m0, s56
	s_nop 0
	global_load_lds_dwordx4 v144, s[82:83]
	s_add_i32 m0, s56, 0x2000
	s_nop 0
	global_load_lds_dwordx4 v162, s[82:83]
	s_waitcnt lgkmcnt(0)
	s_barrier
	v_mfma_f32_16x16x32_bf16 v[140:143], v[204:207], v[80:83], v[140:143]
	v_mfma_f32_16x16x32_bf16 v[80:83], v[228:231], v[80:83], v[108:111]
	v_mfma_f32_16x16x32_bf16 v[140:143], v[222:225], v[84:87], v[140:143]
	v_mfma_f32_16x16x32_bf16 v[80:83], v[232:235], v[84:87], v[80:83]
	v_mfma_f32_16x16x32_bf16 v[84:87], v[204:207], v[88:91], v[136:139]
	v_mfma_f32_16x16x32_bf16 v[88:91], v[228:231], v[88:91], v[104:107]
	v_mfma_f32_16x16x32_bf16 v[100:103], v[228:231], v[188:191], v[100:103]
	v_mfma_f32_16x16x32_bf16 v[104:107], v[204:207], v[196:199], v[128:131]
	v_mfma_f32_16x16x32_bf16 v[96:99], v[228:231], v[196:199], v[96:99]
	v_mfma_f32_16x16x32_bf16 v[84:87], v[222:225], v[92:95], v[84:87]
	v_mfma_f32_16x16x32_bf16 v[88:91], v[232:235], v[92:95], v[88:91]
	v_mfma_f32_16x16x32_bf16 v[92:95], v[204:207], v[188:191], v[132:135]
	v_mfma_f32_16x16x32_bf16 v[100:103], v[232:235], v[192:195], v[100:103]
	v_mfma_f32_16x16x32_bf16 v[128:131], v[222:225], v[200:203], v[104:107]
	v_mfma_f32_16x16x32_bf16 v[96:99], v[232:235], v[200:203], v[96:99]
	v_mfma_f32_16x16x32_bf16 v[92:95], v[222:225], v[192:195], v[92:95]
	s_barrier
	s_mov_b32 m0, s75
	ds_read_b128 v[104:107], v220 offset:16384
	ds_read_b128 v[108:111], v220 offset:17408
	ds_read_b128 v[132:135], v220 offset:18432
	ds_read_b128 v[136:139], v220 offset:19456
	ds_read_b128 v[188:191], v220 offset:20480
	ds_read_b128 v[192:195], v220 offset:21504
	ds_read_b128 v[196:199], v220 offset:22528
	ds_read_b128 v[200:203], v220 offset:23552
	global_load_lds_dwordx4 v144, vcc
	s_mov_b32 m0, s85
	s_nop 0
	global_load_lds_dwordx4 v162, vcc
	s_add_u32 s56, s82, 0x40000
	s_addc_u32 s57, s83, 0
	s_add_i32 s27, s27, s74
	s_mov_b32 m0, s27
	s_nop 0
	global_load_lds_dwordx4 v144, s[56:57]
	s_add_i32 m0, s27, 0x2000
	s_nop 0
	global_load_lds_dwordx4 v162, s[56:57]
	s_waitcnt lgkmcnt(0)
	s_waitcnt vmcnt(6)
	s_barrier
	v_mfma_f32_16x16x32_bf16 v[48:51], v[64:67], v[104:107], v[48:51]
	v_mfma_f32_16x16x32_bf16 v[20:23], v[72:75], v[104:107], v[20:23]
	v_mfma_f32_16x16x32_bf16 v[60:63], v[64:67], v[132:135], v[60:63]
	v_mfma_f32_16x16x32_bf16 v[28:31], v[72:75], v[132:135], v[28:31]
	v_mfma_f32_16x16x32_bf16 v[56:59], v[64:67], v[188:191], v[56:59]
	v_mfma_f32_16x16x32_bf16 v[16:19], v[72:75], v[188:191], v[16:19]
	v_mfma_f32_16x16x32_bf16 v[52:55], v[64:67], v[196:199], v[52:55]
	v_mfma_f32_16x16x32_bf16 v[24:27], v[72:75], v[196:199], v[24:27]
	v_mfma_f32_16x16x32_bf16 v[48:51], v[68:71], v[108:111], v[48:51]
	v_mfma_f32_16x16x32_bf16 v[20:23], v[76:79], v[108:111], v[20:23]
	v_mfma_f32_16x16x32_bf16 v[60:63], v[68:71], v[136:139], v[60:63]
	v_mfma_f32_16x16x32_bf16 v[28:31], v[76:79], v[136:139], v[28:31]
	v_mfma_f32_16x16x32_bf16 v[56:59], v[68:71], v[192:195], v[56:59]
	v_mfma_f32_16x16x32_bf16 v[16:19], v[76:79], v[192:195], v[16:19]
	v_mfma_f32_16x16x32_bf16 v[52:55], v[68:71], v[200:203], v[52:55]
	v_mfma_f32_16x16x32_bf16 v[24:27], v[76:79], v[200:203], v[24:27]
	v_mfma_f32_16x16x32_bf16 v[44:47], v[204:207], v[104:107], v[44:47]
	v_mfma_f32_16x16x32_bf16 v[12:15], v[228:231], v[104:107], v[12:15]
	v_mfma_f32_16x16x32_bf16 v[40:43], v[204:207], v[132:135], v[40:43]
	v_mfma_f32_16x16x32_bf16 v[8:11], v[228:231], v[132:135], v[8:11]
	v_mfma_f32_16x16x32_bf16 v[36:39], v[204:207], v[188:191], v[36:39]
	v_mfma_f32_16x16x32_bf16 v[4:7], v[228:231], v[188:191], v[4:7]
	v_mfma_f32_16x16x32_bf16 v[32:35], v[204:207], v[196:199], v[32:35]
	v_mfma_f32_16x16x32_bf16 v[0:3], v[228:231], v[196:199], v[0:3]
	v_mfma_f32_16x16x32_bf16 v[44:47], v[222:225], v[108:111], v[44:47]
	v_mfma_f32_16x16x32_bf16 v[12:15], v[232:235], v[108:111], v[12:15]
	v_mfma_f32_16x16x32_bf16 v[40:43], v[222:225], v[136:139], v[40:43]
	v_mfma_f32_16x16x32_bf16 v[8:11], v[232:235], v[136:139], v[8:11]
	v_mfma_f32_16x16x32_bf16 v[36:39], v[222:225], v[192:195], v[36:39]
	v_mfma_f32_16x16x32_bf16 v[4:7], v[232:235], v[192:195], v[4:7]
	v_mfma_f32_16x16x32_bf16 v[32:35], v[222:225], v[200:203], v[32:35]
	v_mfma_f32_16x16x32_bf16 v[0:3], v[232:235], v[200:203], v[0:3]
	s_barrier
	s_add_i32 s27, 0, 0x18000
	ds_read_b128 v[64:67], v217 offset:32768
	ds_read_b128 v[68:71], v217 offset:33792
	ds_read_b128 v[72:75], v217 offset:34816
	ds_read_b128 v[76:79], v217 offset:35840
	s_add_u32 s56, vcc_lo, 0x40000
	s_addc_u32 s57, vcc_hi, 0
	s_mov_b32 m0, s98
	ds_read_b128 v[104:107], v220 offset:32768
	ds_read_b128 v[108:111], v220 offset:33792
	ds_read_b128 v[132:135], v220 offset:34816
	ds_read_b128 v[188:191], v220 offset:35840
	ds_read_b128 v[192:195], v220 offset:36864
	ds_read_b128 v[196:199], v220 offset:37888
	ds_read_b128 v[200:203], v220 offset:38912
	ds_read_b128 v[204:207], v220 offset:39936
	global_load_lds_dwordx4 v144, s[56:57]
	s_mov_b32 m0, s29
	s_nop 0
	global_load_lds_dwordx4 v162, s[56:57]
	s_waitcnt lgkmcnt(0)
	s_barrier
	v_mfma_f32_16x16x32_bf16 v[136:139], v[64:67], v[104:107], v[146:149]
	v_mfma_f32_16x16x32_bf16 v[146:149], v[68:71], v[108:111], v[136:139]
	v_mfma_f32_16x16x32_bf16 v[136:139], v[64:67], v[132:135], v[158:161]
	v_mfma_f32_16x16x32_bf16 v[158:161], v[68:71], v[188:191], v[136:139]
	v_mfma_f32_16x16x32_bf16 v[136:139], v[64:67], v[192:195], v[154:157]
	v_mfma_f32_16x16x32_bf16 v[116:119], v[72:75], v[104:107], v[116:119]
	v_mfma_f32_16x16x32_bf16 v[124:127], v[72:75], v[132:135], v[124:127]
	v_mfma_f32_16x16x32_bf16 v[154:157], v[68:71], v[196:199], v[136:139]
	v_mfma_f32_16x16x32_bf16 v[112:115], v[72:75], v[192:195], v[112:115]
	v_mfma_f32_16x16x32_bf16 v[136:139], v[64:67], v[200:203], v[150:153]
	v_mfma_f32_16x16x32_bf16 v[120:123], v[72:75], v[200:203], v[120:123]
	v_mfma_f32_16x16x32_bf16 v[116:119], v[76:79], v[108:111], v[116:119]
	v_mfma_f32_16x16x32_bf16 v[124:127], v[76:79], v[188:191], v[124:127]
	v_mfma_f32_16x16x32_bf16 v[112:115], v[76:79], v[196:199], v[112:115]
	v_mfma_f32_16x16x32_bf16 v[150:153], v[68:71], v[204:207], v[136:139]
	v_mfma_f32_16x16x32_bf16 v[120:123], v[76:79], v[204:207], v[120:123]
	s_barrier
	s_nop 0
	s_add_i32 s58, 0, 0x1c000
	s_add_i32 s27, s27, s74
	ds_read_b128 v[222:225], v217 offset:49152
	ds_read_b128 v[228:231], v217 offset:50176
	ds_read_b128 v[232:235], v217 offset:51200
	ds_read_b128 v[236:239], v217 offset:52224
	s_add_u32 s56, s82, s18
	s_addc_u32 s57, s83, s19
	s_mov_b32 m0, s27
	s_nop 0
	global_load_lds_dwordx4 v144, s[56:57]
	s_add_u32 s56, s82, s18
	s_addc_u32 s57, s83, s19
	s_add_i32 m0, s27, 0x2000
	s_nop 0
	global_load_lds_dwordx4 v162, s[56:57]
	s_waitcnt lgkmcnt(0)
	s_barrier
	v_mfma_f32_16x16x32_bf16 v[136:139], v[222:225], v[104:107], v[140:143]
	v_mfma_f32_16x16x32_bf16 v[80:83], v[232:235], v[104:107], v[80:83]
	v_mfma_f32_16x16x32_bf16 v[140:143], v[228:231], v[108:111], v[136:139]
	v_mfma_f32_16x16x32_bf16 v[108:111], v[236:239], v[108:111], v[80:83]
	v_mfma_f32_16x16x32_bf16 v[80:83], v[222:225], v[132:135], v[84:87]
	v_mfma_f32_16x16x32_bf16 v[136:139], v[228:231], v[188:191], v[80:83]
	v_mfma_f32_16x16x32_bf16 v[80:83], v[232:235], v[132:135], v[88:91]
	v_mfma_f32_16x16x32_bf16 v[104:107], v[236:239], v[188:191], v[80:83]
	v_mfma_f32_16x16x32_bf16 v[80:83], v[222:225], v[192:195], v[92:95]
	v_mfma_f32_16x16x32_bf16 v[132:135], v[228:231], v[196:199], v[80:83]
	v_mfma_f32_16x16x32_bf16 v[80:83], v[232:235], v[192:195], v[100:103]
	v_mfma_f32_16x16x32_bf16 v[100:103], v[236:239], v[196:199], v[80:83]
	v_mfma_f32_16x16x32_bf16 v[80:83], v[222:225], v[200:203], v[128:131]
	v_mfma_f32_16x16x32_bf16 v[128:131], v[228:231], v[204:207], v[80:83]
	v_mfma_f32_16x16x32_bf16 v[80:83], v[232:235], v[200:203], v[96:99]
	v_mfma_f32_16x16x32_bf16 v[96:99], v[236:239], v[204:207], v[80:83]
	s_barrier
	s_nop 0
	s_mov_b32 m0, s31
	s_add_u32 s56, vcc_lo, s18
	s_addc_u32 s57, vcc_hi, s19
	s_nop 2
	ds_read_b128 v[80:83], v220 offset:49152
	ds_read_b128 v[84:87], v220 offset:50176
	ds_read_b128 v[88:91], v220 offset:51200
	ds_read_b128 v[92:95], v220 offset:52224
	ds_read_b128 v[188:191], v220 offset:53248
	ds_read_b128 v[192:195], v220 offset:54272
	ds_read_b128 v[196:199], v220 offset:55296
	ds_read_b128 v[200:203], v220 offset:56320
	global_load_lds_dwordx4 v144, s[56:57]
	s_add_u32 s56, vcc_lo, s18
	s_addc_u32 s57, vcc_hi, s19
	s_mov_b32 m0, s34
	s_nop 0
	global_load_lds_dwordx4 v162, s[56:57]
	s_add_u32 s56, s82, 0x40080
	s_addc_u32 s57, s83, 0
	s_add_i32 s27, s58, s74
	s_mov_b32 m0, s27
	s_nop 0
	global_load_lds_dwordx4 v144, s[56:57]
	s_add_i32 m0, s27, 0x2000
	s_nop 0
	global_load_lds_dwordx4 v162, s[56:57]
	s_waitcnt lgkmcnt(0)
	s_waitcnt vmcnt(6)
	s_barrier
	v_mfma_f32_16x16x32_bf16 v[48:51], v[64:67], v[80:83], v[48:51]
	v_mfma_f32_16x16x32_bf16 v[20:23], v[72:75], v[80:83], v[20:23]
	v_mfma_f32_16x16x32_bf16 v[60:63], v[64:67], v[88:91], v[60:63]
	v_mfma_f32_16x16x32_bf16 v[28:31], v[72:75], v[88:91], v[28:31]
	v_mfma_f32_16x16x32_bf16 v[56:59], v[64:67], v[188:191], v[56:59]
	v_mfma_f32_16x16x32_bf16 v[16:19], v[72:75], v[188:191], v[16:19]
	v_mfma_f32_16x16x32_bf16 v[52:55], v[64:67], v[196:199], v[52:55]
	v_mfma_f32_16x16x32_bf16 v[24:27], v[72:75], v[196:199], v[24:27]
	v_mfma_f32_16x16x32_bf16 v[48:51], v[68:71], v[84:87], v[48:51]
	v_mfma_f32_16x16x32_bf16 v[20:23], v[76:79], v[84:87], v[20:23]
	v_mfma_f32_16x16x32_bf16 v[60:63], v[68:71], v[92:95], v[60:63]
	v_mfma_f32_16x16x32_bf16 v[28:31], v[76:79], v[92:95], v[28:31]
	v_mfma_f32_16x16x32_bf16 v[56:59], v[68:71], v[192:195], v[56:59]
	v_mfma_f32_16x16x32_bf16 v[16:19], v[76:79], v[192:195], v[16:19]
	v_mfma_f32_16x16x32_bf16 v[52:55], v[68:71], v[200:203], v[52:55]
	v_mfma_f32_16x16x32_bf16 v[24:27], v[76:79], v[200:203], v[24:27]
	v_mfma_f32_16x16x32_bf16 v[44:47], v[222:225], v[80:83], v[44:47]
	v_mfma_f32_16x16x32_bf16 v[12:15], v[232:235], v[80:83], v[12:15]
	v_mfma_f32_16x16x32_bf16 v[40:43], v[222:225], v[88:91], v[40:43]
	v_mfma_f32_16x16x32_bf16 v[8:11], v[232:235], v[88:91], v[8:11]
	v_mfma_f32_16x16x32_bf16 v[36:39], v[222:225], v[188:191], v[36:39]
	v_mfma_f32_16x16x32_bf16 v[4:7], v[232:235], v[188:191], v[4:7]
	v_mfma_f32_16x16x32_bf16 v[32:35], v[222:225], v[196:199], v[32:35]
	v_mfma_f32_16x16x32_bf16 v[0:3], v[232:235], v[196:199], v[0:3]
	v_mfma_f32_16x16x32_bf16 v[44:47], v[228:231], v[84:87], v[44:47]
	v_mfma_f32_16x16x32_bf16 v[12:15], v[236:239], v[84:87], v[12:15]
	v_mfma_f32_16x16x32_bf16 v[40:43], v[228:231], v[92:95], v[40:43]
	v_mfma_f32_16x16x32_bf16 v[8:11], v[236:239], v[92:95], v[8:11]
	v_mfma_f32_16x16x32_bf16 v[36:39], v[228:231], v[192:195], v[36:39]
	v_mfma_f32_16x16x32_bf16 v[4:7], v[236:239], v[192:195], v[4:7]
	v_mfma_f32_16x16x32_bf16 v[32:35], v[228:231], v[200:203], v[32:35]
	v_mfma_f32_16x16x32_bf16 v[0:3], v[236:239], v[200:203], v[0:3]
	s_barrier
	s_add_i32 s37, s37, 2
	s_add_u32 s86, s86, 0x100
	s_addc_u32 s87, s87, 0
	s_add_u32 s33, s33, 0x100
	s_addc_u32 s36, s36, 0
	s_cmp_gt_u32 s37, 13
	s_cbranch_scc0 .LBB0_125
	s_lshl_b32 s1, s84, 8
	v_readlane_b32 s10, v254, 61
	s_add_i32 s1, s1, s10
	v_or_b32_e32 v198, s1, v216
	s_add_i32 s10, s1, 0x80
	v_or_b32_e32 v168, s10, v216
	v_lshl_or_b32 v188, s0, 7, v219
	v_lshlrev_b32_e32 v190, 2, v188
	v_lshlrev_b32_e32 v189, 1, v188
	s_ashr_i32 s11, s1, 5
	s_movk_i32 s10, 0xb00
	s_movk_i32 s20, 0x1600
	s_mov_b32 s101, 0xbfb8aa3b
	s_cmp_eq_u32 s84, s100
	s_cbranch_scc1 .Ldepi_w
	v_ashrrev_i32_e32 v199, 31, v198
	v_ashrrev_i32_e32 v169, 31, v168
	v_lshl_add_u64 v[170:171], v[198:199], 3, s[48:49]
	v_lshl_add_u64 v[172:173], v[168:169], 3, s[48:49]
	global_load_dwordx2 v[176:177], v[170:171], off
	global_load_dwordx2 v[202:203], v[170:171], off offset:128
	global_load_dwordx2 v[206:207], v[170:171], off offset:256
	global_load_dwordx2 v[222:223], v[170:171], off offset:384
	global_load_dwordx2 v[200:201], v[172:173], off
	global_load_dwordx2 v[196:197], v[172:173], off offset:128
	global_load_dwordx2 v[194:195], v[172:173], off offset:256
	global_load_dwordx2 v[192:193], v[172:173], off offset:384
